# nt hint on the final f32 output stores of the last row phase
# speedup vs baseline: 1.0025x; 1.0025x over previous
.LBB0_301:
	s_or_b64 exec, exec, s[2:3]
	v_pk_mul_f32 v[110:111], v[36:37], v[36:37]
	v_pk_mul_f32 v[112:113], v[32:33], v[32:33]
	v_pk_mul_f32 v[106:107], v[38:39], v[38:39]
	v_pk_mul_f32 v[108:109], v[34:35], v[34:35]
	v_mov_b32_e32 v114, v110
	v_mov_b32_e32 v115, v112
	v_mov_b32_e32 v112, v111
	v_pk_mul_f32 v[102:103], v[10:11], v[10:11]
	v_pk_mul_f32 v[104:105], v[8:9], v[8:9]
	v_pk_add_f32 v[110:111], v[114:115], v[112:113]
	v_mov_b32_e32 v112, v106
	v_mov_b32_e32 v113, v108
	v_mov_b32_e32 v108, v107
	v_pk_add_f32 v[106:107], v[112:113], v[108:109]
	v_pk_mov_b32 v[108:109], v[104:105], v[102:103] op_sel:[1,0]
	v_mov_b32_e32 v105, v103
	v_pk_add_f32 v[102:103], v[108:109], v[104:105]
	v_pk_add_f32 v[106:107], v[110:111], v[106:107]
	v_pk_add_f32 v[102:103], v[102:103], v[102:103] op_sel_hi:[0,1]
	v_mul_f32_e32 v102, v12, v12
	v_pk_fma_f32 v[104:105], v[12:13], v[12:13], v[102:103] op_sel_hi:[1,1,0]
	v_mul_f32_e32 v102, v14, v14
	v_pk_add_f32 v[106:107], v[106:107], v[106:107] op_sel_hi:[0,1]
	v_pk_fma_f32 v[108:109], v[14:15], v[14:15], v[102:103] op_sel_hi:[1,1,0]
	v_mul_f32_e32 v104, v16, v16
	v_mul_f32_e32 v108, v17, v17
	v_mul_f32_e32 v102, v18, v18
	v_mul_f32_e32 v106, v19, v19
	v_pk_mul_f32 v[98:99], v[22:23], v[22:23]
	v_pk_mul_f32 v[100:101], v[20:21], v[20:21]
	v_pk_add_f32 v[104:105], v[104:105], v[108:109]
	v_pk_add_f32 v[102:103], v[102:103], v[106:107]
	v_min_i32_e32 v48, 0x2000, v84
	v_pk_add_f32 v[102:103], v[104:105], v[102:103]
	v_pk_mov_b32 v[104:105], v[100:101], v[98:99] op_sel:[1,0]
	v_mov_b32_e32 v101, v99
	v_pk_add_f32 v[98:99], v[104:105], v[100:101]
	v_ashrrev_i32_e32 v62, 11, v48
	v_pk_add_f32 v[98:99], v[98:99], v[98:99] op_sel_hi:[0,1]
	v_readlane_b32 s2, v255, 8
	v_mul_f32_e32 v98, v24, v24
	s_waitcnt vmcnt(0)
	v_lshlrev_b32_e32 v58, 16, v46
	v_and_b32_e32 v59, 0xffff0000, v46
	v_lshlrev_b32_e32 v60, 16, v47
	v_and_b32_e32 v61, 0xffff0000, v47
	v_lshlrev_b32_e32 v46, 16, v40
	v_and_b32_e32 v47, 0xffff0000, v40
	v_lshlrev_b32_e32 v48, 16, v41
	v_and_b32_e32 v49, 0xffff0000, v41
	v_mul_hi_i32_i24_e32 v41, 0xc000, v62
	v_mul_i32_i24_e32 v40, 0xc000, v62
	v_readlane_b32 s3, v255, 9
	v_pk_fma_f32 v[100:101], v[24:25], v[24:25], v[98:99] op_sel_hi:[1,1,0]
	v_mul_f32_e32 v98, v26, v26
	v_lshlrev_b32_e32 v50, 16, v42
	v_and_b32_e32 v51, 0xffff0000, v42
	v_lshlrev_b32_e32 v52, 16, v43
	v_and_b32_e32 v53, 0xffff0000, v43
	v_lshl_add_u64 v[62:63], s[2:3], 0, v[40:41]
	v_lshlrev_b64 v[42:43], 2, v[88:89]
	v_pk_add_f32 v[102:103], v[102:103], v[102:103] op_sel_hi:[0,1]
	v_pk_fma_f32 v[104:105], v[26:27], v[26:27], v[98:99] op_sel_hi:[1,1,0]
	v_lshl_add_u64 v[62:63], v[62:63], 0, v[42:43]
	s_mov_b64 s[2:3], 0xa000
	v_mul_f32_e32 v100, v28, v28
	v_mul_f32_e32 v104, v29, v29
	v_mul_f32_e32 v98, v30, v30
	v_mul_f32_e32 v102, v31, v31
	v_lshl_add_u64 v[82:83], v[62:63], 0, s[2:3]
	s_mov_b32 s2, 0xb000
	v_pk_add_f32 v[100:101], v[100:101], v[104:105]
	v_pk_add_f32 v[98:99], v[98:99], v[102:103]
	v_add_co_u32_e32 v96, vcc, s2, v62
	v_pk_add_f32 v[98:99], v[100:101], v[98:99]
	v_and_b32_e32 v93, 64, v229
	v_lshlrev_b32_e32 v56, 16, v45
	v_and_b32_e32 v57, 0xffff0000, v45
	v_addc_co_u32_e32 v97, vcc, 0, v63, vcc
	v_add_f32_e32 v45, v98, v99
	v_add_u32_e32 v99, 64, v93
	v_xor_b32_e32 v93, 1, v229
	v_cmp_lt_i32_e32 vcc, v93, v99
	v_lshl_add_u64 v[94:95], s[10:11], 0, v[42:43]
	global_load_dwordx4 v[62:65], v[96:97], off offset:-4096
	global_load_dwordx4 v[66:69], v[94:95], off
	global_load_dwordx4 v[70:73], v[94:95], off offset:1024
	global_load_dwordx4 v[74:77], v[82:83], off offset:1024
	global_load_dwordx4 v[78:81], v[82:83], off offset:2048
	v_cndmask_b32_e32 v93, v229, v93, vcc
	v_lshlrev_b32_e32 v98, 2, v93
	ds_bpermute_b32 v93, v98, v45
	global_load_dwordx4 v[100:103], v[82:83], off offset:3072
	global_load_dwordx4 v[104:107], v[94:95], off offset:2048
	global_load_dwordx4 v[108:111], v[94:95], off offset:3072
	global_load_dwordx4 v[112:115], v[96:97], off
	v_xor_b32_e32 v82, 2, v229
	v_cmp_lt_i32_e32 vcc, v82, v99
	v_lshlrev_b32_e32 v54, 16, v44
	s_waitcnt lgkmcnt(0)
	v_add_f32_e32 v45, v45, v93
	v_cndmask_b32_e32 v82, v229, v82, vcc
	v_lshlrev_b32_e32 v93, 2, v82
	ds_bpermute_b32 v128, v93, v45
	v_add_co_u32_e32 v82, vcc, s30, v94
	v_and_b32_e32 v55, 0xffff0000, v44
	s_nop 0
	v_addc_co_u32_e32 v83, vcc, 0, v95, vcc
	s_waitcnt lgkmcnt(0)
	v_add_f32_e32 v95, v45, v128
	v_xor_b32_e32 v45, 4, v229
	v_cmp_lt_i32_e32 vcc, v45, v99
	global_load_dwordx4 v[116:119], v[82:83], off
	global_load_dwordx4 v[120:123], v[96:97], off offset:1024
	global_load_dwordx4 v[124:127], v[82:83], off offset:1024
	v_cndmask_b32_e32 v45, v229, v45, vcc
	v_lshlrev_b32_e32 v94, 2, v45
	ds_bpermute_b32 v140, v94, v95
	global_load_dwordx4 v[128:131], v[96:97], off offset:2048
	global_load_dwordx4 v[132:135], v[82:83], off offset:2048
	global_load_dwordx4 v[136:139], v[82:83], off offset:3072
	v_lshlrev_b32_e32 v44, 16, v6
	v_and_b32_e32 v45, 0xffff0000, v6
	v_xor_b32_e32 v82, 8, v229
	s_waitcnt lgkmcnt(0)
	v_add_f32_e32 v6, v95, v140
	global_load_dwordx4 v[140:143], v[96:97], off offset:3072
	v_cmp_lt_i32_e32 vcc, v82, v99
	v_and_b32_e32 v83, 0xffff0000, v7
	v_lshlrev_b32_e32 v146, 16, v5
	v_cndmask_b32_e32 v82, v229, v82, vcc
	v_lshlrev_b32_e32 v95, 2, v82
	ds_bpermute_b32 v145, v95, v6
	v_lshlrev_b32_e32 v82, 16, v7
	v_xor_b32_e32 v7, 16, v229
	v_cmp_lt_i32_e32 vcc, v7, v99
	v_and_b32_e32 v147, 0xffff0000, v5
	s_waitcnt lgkmcnt(0)
	v_add_f32_e32 v6, v6, v145
	v_cndmask_b32_e32 v7, v229, v7, vcc
	v_lshlrev_b32_e32 v96, 2, v7
	ds_bpermute_b32 v7, v96, v6
	v_xor_b32_e32 v5, 32, v229
	v_cmp_lt_i32_e32 vcc, v5, v99
	v_lshlrev_b32_e32 v144, 16, v4
	v_and_b32_e32 v145, 0xffff0000, v4
	v_cndmask_b32_e32 v5, v229, v5, vcc
	s_waitcnt lgkmcnt(0)
	v_add_f32_e32 v4, v6, v7
	v_lshlrev_b32_e32 v97, 2, v5
	ds_bpermute_b32 v5, v97, v4
	v_lshlrev_b32_e32 v148, 16, v2
	v_and_b32_e32 v149, 0xffff0000, v2
	v_lshlrev_b32_e32 v150, 16, v3
	v_and_b32_e32 v151, 0xffff0000, v3
	s_waitcnt lgkmcnt(0)
	v_add_f32_e32 v2, v4, v5
	v_fmamk_f32 v2, v2, 0x3a000000, v227
	v_mul_f32_e32 v3, 0x4b800000, v2
	v_cmp_gt_f32_e32 vcc, s96, v2
	v_lshlrev_b32_e32 v152, 16, v0
	v_and_b32_e32 v153, 0xffff0000, v0
	v_cndmask_b32_e32 v2, v2, v3, vcc
	v_rsq_f32_e32 v2, v2
	v_lshlrev_b32_e32 v154, 16, v1
	v_and_b32_e32 v155, 0xffff0000, v1
	v_readlane_b32 s4, v255, 6
	v_mul_f32_e32 v0, 0x45800000, v2
	v_cndmask_b32_e32 v156, v2, v0, vcc
	v_pk_mul_f32 v[0:1], v[38:39], v[156:157] op_sel_hi:[1,0]
	v_pk_mul_f32 v[2:3], v[36:37], v[156:157] op_sel_hi:[1,0]
	v_pk_mul_f32 v[6:7], v[32:33], v[156:157] op_sel_hi:[1,0]
	v_pk_mul_f32 v[10:11], v[10:11], v[156:157] op_sel_hi:[1,0]
	v_pk_mul_f32 v[8:9], v[8:9], v[156:157] op_sel_hi:[1,0]
	v_pk_mul_f32 v[14:15], v[14:15], v[156:157] op_sel_hi:[1,0]
	v_pk_mul_f32 v[12:13], v[12:13], v[156:157] op_sel_hi:[1,0]
	v_pk_mul_f32 v[18:19], v[18:19], v[156:157] op_sel_hi:[1,0]
	s_waitcnt vmcnt(14)
	v_pk_mul_f32 v[4:5], v[66:67], v[2:3]
	v_pk_mul_f32 v[0:1], v[68:69], v[0:1]
	v_pk_mul_f32 v[16:17], v[16:17], v[156:157] op_sel_hi:[1,0]
	v_pk_fma_f32 v[2:3], v[64:65], v[0:1], v[60:61]
	v_pk_fma_f32 v[0:1], v[62:63], v[4:5], v[58:59]
	v_pk_mul_f32 v[4:5], v[34:35], v[156:157] op_sel_hi:[1,0]
	v_pk_mul_f32 v[22:23], v[22:23], v[156:157] op_sel_hi:[1,0]
	v_pk_mul_f32 v[20:21], v[20:21], v[156:157] op_sel_hi:[1,0]
	v_pk_mul_f32 v[26:27], v[26:27], v[156:157] op_sel_hi:[1,0]
	v_pk_mul_f32 v[24:25], v[24:25], v[156:157] op_sel_hi:[1,0]
	v_pk_mul_f32 v[30:31], v[30:31], v[156:157] op_sel_hi:[1,0]
	v_pk_mul_f32 v[28:29], v[28:29], v[156:157] op_sel_hi:[1,0]
	s_waitcnt vmcnt(13)
	v_pk_mul_f32 v[32:33], v[70:71], v[6:7]
	v_pk_mul_f32 v[4:5], v[72:73], v[4:5]
	s_waitcnt vmcnt(9)
	v_pk_mul_f32 v[8:9], v[104:105], v[8:9]
	v_pk_mul_f32 v[10:11], v[106:107], v[10:11]
	s_waitcnt vmcnt(8)
	v_pk_mul_f32 v[12:13], v[108:109], v[12:13]
	v_pk_mul_f32 v[14:15], v[110:111], v[14:15]
	v_readlane_b32 s5, v255, 7
	v_pk_fma_f32 v[6:7], v[76:77], v[4:5], v[56:57]
	v_pk_fma_f32 v[4:5], v[74:75], v[32:33], v[54:55]
	s_waitcnt vmcnt(6)
	v_pk_mul_f32 v[16:17], v[116:117], v[16:17]
	v_pk_mul_f32 v[18:19], v[118:119], v[18:19]
	s_waitcnt vmcnt(4)
	v_pk_mul_f32 v[20:21], v[124:125], v[20:21]
	v_pk_mul_f32 v[22:23], v[126:127], v[22:23]
	v_pk_fma_f32 v[10:11], v[80:81], v[10:11], v[52:53]
	s_waitcnt vmcnt(2)
	v_pk_mul_f32 v[24:25], v[132:133], v[24:25]
	v_pk_mul_f32 v[26:27], v[134:135], v[26:27]
	s_waitcnt vmcnt(1)
	v_pk_mul_f32 v[28:29], v[136:137], v[28:29]
	v_pk_mul_f32 v[30:31], v[138:139], v[30:31]
	v_pk_fma_f32 v[8:9], v[78:79], v[8:9], v[50:51]
	v_pk_fma_f32 v[14:15], v[102:103], v[14:15], v[48:49]
	v_pk_fma_f32 v[12:13], v[100:101], v[12:13], v[46:47]
	v_pk_fma_f32 v[18:19], v[114:115], v[18:19], v[82:83]
	v_pk_fma_f32 v[16:17], v[112:113], v[16:17], v[44:45]
	v_pk_fma_f32 v[22:23], v[122:123], v[22:23], v[146:147]
	v_pk_fma_f32 v[20:21], v[120:121], v[20:21], v[144:145]
	v_pk_fma_f32 v[26:27], v[130:131], v[26:27], v[150:151]
	v_pk_fma_f32 v[24:25], v[128:129], v[24:25], v[148:149]
	s_waitcnt vmcnt(0)
	v_pk_fma_f32 v[30:31], v[142:143], v[30:31], v[154:155]
	v_pk_fma_f32 v[28:29], v[140:141], v[28:29], v[152:153]
	s_mov_b64 s[2:3], -1
	s_and_b64 vcc, exec, s[4:5]
	s_cbranch_vccz .LBB0_303
	v_readlane_b32 s2, v252, 6
	v_mov_b32_e32 v35, s25
	v_cndmask_b32_e64 v33, 0, v85, s[36:37]
	v_mov_b32_e32 v34, s2
	v_readlane_b32 s2, v252, 5
	v_cndmask_b32_e64 v32, v192, v84, s[36:37]
	v_cndmask_b32_e64 v35, v34, v35, s[36:37]
	v_mov_b32_e32 v34, s2
	v_mov_b32_e32 v36, s24
	v_cndmask_b32_e64 v34, v34, v36, s[36:37]
	v_lshlrev_b64 v[32:33], 13, v[32:33]
	v_lshl_add_u64 v[32:33], v[34:35], 0, v[32:33]
	v_lshl_add_u64 v[32:33], v[88:89], 2, v[32:33]
	global_store_dwordx4 v[32:33], v[0:3], off nt
	global_store_dwordx4 v[32:33], v[4:7], off offset:1024 nt
	global_store_dwordx4 v[32:33], v[8:11], off offset:2048 nt
	global_store_dwordx4 v[32:33], v[12:15], off offset:3072 nt
	v_add_co_u32_e32 v32, vcc, 0x1000, v32
	s_mov_b64 s[2:3], 0
	s_nop 0
	v_addc_co_u32_e32 v33, vcc, 0, v33, vcc
	global_store_dwordx4 v[32:33], v[16:19], off nt
	global_store_dwordx4 v[32:33], v[20:23], off offset:1024 nt
	global_store_dwordx4 v[32:33], v[24:27], off offset:2048 nt
	global_store_dwordx4 v[32:33], v[28:31], off offset:3072 nt
